# v21: v19 + L2 warm-up loads for the next GLA item, issued after the current item's last load wait (M1, M3 GLA, RG-LRU unit) so they do not extend that wait
# speedup vs baseline: 1.0086x; 1.0086x over previous
; DI UnitInfo decode_unit(int unit) {
;     UnitInfo u;
;     if (unit < NUNIT_P) { u.prompt = 1; u.b = unit / NCH; u.c = unit - u.b * NCH; u.s = 0; const int tau0 = u.c == 0 ? 0 : NMETA + 64 * (u.c - 1); u.nvalid = u.c == 0 ? NMETA : 64; u.row0 = u.b * LP + tau0; }
;     else { u.prompt = 0; u.s = unit - NUNIT_P; u.b = 0; u.c = 0; u.row0 = MP + LS * u.s; u.nvalid = LS; }
;     return u;
; template <bool FINAL>
; DI void gla_unit(KA a, int l, int item, LAS unsigned char* lds) {
;     ...
;         for (int jj = 0; jj < 8; ++jj) {
;             const int t = 8 * tg + jj;
;             float ga = 0.f, gb = 0.f;
;             if (t < nvalid) {
;                 const u32x4* lp = (const u32x4*)(U + (size_t)(row0 + t) * UN + U_LR);
;                 float lr[16]; unpack8(lp[0], lr); unpack8(lp[1], lr + 8);
;                 float za = bg[0], zb = bg[1];
; #pragma unroll
;                 for (int e = 0; e < 16; ++e) { za += wg[0][e] * lr[e]; zb += wg[1][e] * lr[e]; }
;                 ga = (fminf(za, 0.f) - __logf(1.f + __expf(-fabsf(za)))) * (1.f / 16.f);
;                 gb = (fminf(zb, 0.f) - __logf(1.f + __expf(-fabsf(zb)))) * (1.f / 16.f);
;             }
;             run0 += ga; run1 += gb; bl[0][jj] = run0; bl[1][jj] = run1;
;         }
.LBB0_665:
	v_mov_b32_e32 v16, v43
	s_waitcnt vmcnt(24)
	v_pk_add_f32 v[30:31], v[20:21], v[16:17]
	v_mov_b32_e32 v16, v21
	s_waitcnt vmcnt(20)
	v_pk_add_f32 v[24:25], v[16:17], v[42:43]
	v_mov_b32_e32 v16, v47
	s_waitcnt vmcnt(1)
	s_add_i32 s72, s33, 0x100
	s_cmpk_gt_i32 s72, 0x30f
	s_cbranch_scc1 .Lwm1_end
	s_add_u32 s84, s28, 0x5000000
	s_addc_u32 s85, s29, 0
	s_lshl_b32 s86, s47, 3
	s_lshr_b32 s73, s72, 1
	s_and_b32 s74, s72, 1
	s_cmpk_lt_u32 s73, 0x108
	s_cbranch_scc0 .Lwm1_samp
	s_mul_i32 s75, s73, 0xf83f
	s_lshr_b32 s75, s75, 21
	s_mul_i32 s76, s75, 0xffffffdf
	s_add_i32 s76, s76, s73
	s_lshl_b32 s77, s76, 6
	s_sub_i32 s77, s77, 48
	s_cmp_eq_u32 s76, 0
	s_cselect_b32 s77, 0, s77
	s_cselect_b32 s78, 15, 63
	s_cselect_b32 s79, 0, 1
	s_mulk_i32 s75, 0x810
	s_add_i32 s77, s77, s75
	s_branch .Lwm1_go

; template <bool FINAL>
; DI void gla_unit(KA a, int l, int item, LAS unsigned char* lds) {
;     ...
;     for (int hh = 0; hh < 2; ++hh) {
;         const int hd = 2 * hp + hh;
; #pragma unroll
;         for (int jj = 0; jj < 8; ++jj) {
;             const int t = 8 * tg + jj; kraw[hh][jj] = 0u; qraw[hh][jj] = 0u;
;             if (t < nvalid) { kraw[hh][jj] = U[(size_t)(row0 + t) * UN + U_K + hd * 64 + dk]; if (FINAL) qraw[hh][jj] = U[(size_t)(row0 + t) * UN + U_Q + hd * 64 + dk]; }
;         }
;         v0[hh] = (u32x4){0u, 0u, 0u, 0u}; v1[hh] = v0[hh]; g0[hh] = v0[hh]; g1[hh] = v0[hh];
;         if (vj < nvalid) {
;             const u32x4* vp = (const u32x4*)(U + (size_t)(row0 + vj) * UN + U_V + hd * 128 + vdvc); v0[hh] = vp[0]; v1[hh] = vp[1];
;             if (FINAL) { const u32x4* gp = (const u32x4*)(U + (size_t)(row0 + vj) * UN + U_GO + hd * 128 + vdvc); g0[hh] = gp[0]; g1[hh] = gp[1]; }
;         }
.Lwm1_go:
	v_and_b32_e32 v130, 7, v75
	v_lshrrev_b32_e32 v131, 3, v75
	v_add_u32_e32 v131, s86, v131
	s_lshl_b32 s80, s74, 8
	s_lshl_b32 s81, s74, 9
	v_lshlrev_b32_e32 v132, 7, v130
	s_add_i32 s75, s80, 0xa00
	v_mov_b32_e32 v133, s75
	s_add_i32 s75, s81, 0xb00
	v_mov_b32_e32 v134, s75
	v_cmp_gt_u32_e32 vcc, 2, v130
	s_nop 1
	v_cndmask_b32_e32 v133, v134, v133, vcc
	v_add_u32_e32 v132, v132, v133
	v_mov_b32_e32 v134, 0x1400
	v_cmp_gt_u32_e32 vcc, 6, v130
	s_nop 1
	v_cndmask_b32_e32 v132, v134, v132, vcc
	v_min_u32_e32 v135, s78, v131
	v_add_u32_e32 v135, s77, v135
	v_mul_u32_u24_e32 v135, 0x1600, v135
	v_add_u32_e32 v135, v135, v132
	global_load_dword v136, v135, s[84:85]
; #define LAS __attribute__((address_space(3)))
; template <bool FINAL>
; DI void gla_unit(KA a, int l, int item, LAS unsigned char* lds) {
;     ...
;             run0 += ga; run1 += gb; bl[0][jj] = run0; bl[1][jj] = run1;
;         }
;         ((LAS float*)(lds + GL_GSUM))[tg * 64 + dk] = run0;
;         ((LAS float*)(lds + GL_HEAD + GL_GSUM))[tg * 64 + dk] = run1;
;     }
; #pragma unroll
;     for (int hh = 0; hh < 2; ++hh) {
;         LAS bf16_t* vT = (LAS bf16_t*)(lds + hh * GL_HEAD + GL_VT); LAS bf16_t* sT = (LAS bf16_t*)(lds + hh * GL_HEAD + GL_ST);
;         {
;             const unsigned vv[8] = {v0[hh].x, v0[hh].y, v0[hh].z, v0[hh].w, v1[hh].x, v1[hh].y, v1[hh].z, v1[hh].w};
;             const int col = ((((vj >> 3) ^ ((vdvc >> 4) & 7)) << 3) | (vj & 7));
; #pragma unroll
;             for (int e = 0; e < 8; ++e) { vT[(vdvc + 2 * e) * 72 + col] = (bf16_t)(vv[e] & 0xffffu); vT[(vdvc + 2 * e + 1) * 72 + col] = (bf16_t)(vv[e] >> 16); }
;         }
;         if (FINAL) {
; #pragma unroll
;             for (int it = 0; it < 4; ++it) {
;                 const int idx = it * 512 + tid, dkk = idx >> 5, dv4 = (idx & 31) * 4;
;                 const int col = ((((dkk >> 3) ^ ((dv4 >> 4) & 7)) << 3) | (dkk & 7));
;                 sT[(dv4 + 0) * 72 + col] = f2bf(sv[hh][it].x); sT[(dv4 + 1) * 72 + col] = f2bf(sv[hh][it].y); sT[(dv4 + 2) * 72 + col] = f2bf(sv[hh][it].z); sT[(dv4 + 3) * 72 + col] = f2bf(sv[hh][it].w);
;             }
;         }
;     }
;     LBAR();
; #pragma unroll
;     for (int hh = 0; hh < 2; ++hh) {
;         LAS float* gsum = (LAS float*)(lds + hh * GL_HEAD + GL_GSUM); LAS float* dS = (LAS float*)(lds + hh * GL_HEAD + GL_DS);
;         LAS bf16_t* qs = (LAS bf16_t*)(lds + hh * GL_HEAD + GL_QS); LAS bf16_t* ks = (LAS bf16_t*)(lds + hh * GL_HEAD + GL_KS);
;         float prefix = 0.f, blast = 0.f;
; #pragma unroll
;         for (int g2 = 0; g2 < 8; ++g2) { const float v = gsum[g2 * 64 + dk]; blast += v; if (g2 < tg) prefix += v; }
; #pragma unroll
;         for (int jj = 0; jj < 8; ++jj) {
;             const int t = 8 * tg + jj;
;             const float bj = prefix + bl[hh][jj];
;             const float kv = bf2f(kraw[hh][jj]);
;             if (FINAL) { qs[t * 72 + dk] = f2bf(bf2f(qraw[hh][jj]) * 0.125f * __expf(bj)); ks[t * 72 + dk] = f2bf(kv * __expf(-bj)); }
;             else ks[dk * 72 + t] = f2bf(kv * __expf(blast - bj));
;         }
.Lwm1_end:
	v_pk_add_f32 v[28:29], v[24:25], v[46:47]
	v_pk_add_f32 v[32:33], v[30:31], v[16:17]
	v_mov_b32_e32 v16, v45
	v_pk_add_f32 v[26:27], v[28:29], v[44:45]
	v_pk_add_f32 v[34:35], v[32:33], v[16:17]
	v_pk_add_f32 v[22:23], v[26:27], v[50:51]
	s_and_b32 s0, s48, 0x3fffffc0
	v_pk_add_f32 v[18:19], v[22:23], v[48:49]
	v_add_f32_e32 v23, v34, v51
	v_add_f32_e32 v25, v23, v49
	v_add_f32_e32 v27, v25, v55
	v_or_b32_e32 v29, s0, v75
	v_pk_add_f32 v[16:17], v[18:19], v[54:55]
	v_add_f32_e32 v19, v27, v53
	v_lshl_add_u32 v29, v29, 2, 0
	v_add_f32_e32 v17, v16, v52
	ds_write_b32 v29, v19
	v_add_u32_e32 v29, 0x10c00, v29
	ds_write_b32 v29, v17
	v_ashrrev_i32_e32 v29, 6, v107
	v_lshrrev_b32_e32 v33, 2, v107
	v_bitop3_b32 v29, v29, v107, 7 bitop3:0x78
	v_and_b32_e32 v33, 14, v33
	v_mul_u32_u24_e32 v31, 0x90, v108
	v_lshl_or_b32 v29, v29, 4, v33
	v_add3_u32 v31, 0, v31, v29
	v_readlane_b32 s4, v254, 47
	ds_write_b16 v31, v4 offset:22528
	ds_write_b16_d16_hi v31, v4 offset:22672
	s_movk_i32 s0, 0x90
	ds_write_b16 v31, v5 offset:22816
	ds_write_b16_d16_hi v31, v5 offset:22960
	ds_write_b16 v31, v6 offset:23104
	ds_write_b16_d16_hi v31, v6 offset:23248
	ds_write_b16 v31, v7 offset:23392
	ds_write_b16_d16_hi v31, v7 offset:23536
	ds_write_b16 v31, v0 offset:23680
	ds_write_b16_d16_hi v31, v0 offset:23824
	ds_write_b16 v31, v1 offset:23968
	ds_write_b16_d16_hi v31, v1 offset:24112
	ds_write_b16 v31, v2 offset:24256
	ds_write_b16_d16_hi v31, v2 offset:24400
	ds_write_b16 v31, v3 offset:24544
	ds_write_b16_d16_hi v31, v3 offset:24688
	v_add_u32_e32 v3, s4, v29
	v_mad_u32_u24 v4, v108, s0, v223
	v_mad_u32_u24 v31, v108, s0, v3
	v_mad_u32_u24 v5, v108, s0, v224
	ds_write_b16 v31, v12
	ds_write_b16_d16_hi v31, v12 offset:144
	v_add_u32_e32 v12, v3, v4
	v_add3_u32 v4, s4, v4, v29
	ds_write_b16_d16_hi v4, v13 offset:144
	v_add_u32_e32 v4, v3, v5
	v_mad_u32_u24 v6, v108, s0, v225
	ds_write_b16 v4, v14
	v_add3_u32 v4, s4, v5, v29
	ds_write_b16_d16_hi v4, v14 offset:144
	v_add_u32_e32 v4, v3, v6
	v_mad_u32_u24 v7, v108, s0, v226
	ds_write_b16 v4, v15
	v_add3_u32 v4, s4, v6, v29
	ds_write_b16_d16_hi v4, v15 offset:144
	v_add_u32_e32 v4, v3, v7
	v_mad_u32_u24 v0, v108, s0, v227
	ds_write_b16 v4, v8
	v_add3_u32 v4, s4, v7, v29
	v_mad_u32_u24 v1, v108, s0, v228
	ds_write_b16_d16_hi v4, v8 offset:144
	v_add_u32_e32 v4, v3, v0
	v_add3_u32 v0, s4, v0, v29
	ds_write_b16_d16_hi v0, v9 offset:144
	v_add_u32_e32 v0, v3, v1
	v_mad_u32_u24 v2, v108, s0, v229
	ds_write_b16 v0, v10
	v_add3_u32 v0, s4, v1, v29
	ds_write_b16_d16_hi v0, v10 offset:144
	v_add_u32_e32 v0, v3, v2
	ds_write_b16 v0, v11
	v_add3_u32 v0, s4, v2, v29
	ds_write_b16 v12, v13
	ds_write_b16 v4, v9
	ds_write_b16_d16_hi v0, v11 offset:144
	s_waitcnt lgkmcnt(0)
	s_barrier
	v_add_u32_e32 v10, 0, v144
	s_lshl_b32 s0, s47, 4
	ds_read2st64_b32 v[2:3], v10 offset1:1
	s_cmp_lt_u32 s48, 64
	s_cselect_b64 s[6:7], -1, 0
	s_lshl_b32 s26, s50, 2
	s_or_b32 s4, s26, s49
	s_cmp_gt_i32 s47, 0
	s_waitcnt lgkmcnt(0)
	v_add_f32_e32 v2, 0, v2
	s_cselect_b64 s[22:23], -1, 0
	ds_read2st64_b32 v[4:5], v10 offset0:2 offset1:3
	ds_read2st64_b32 v[6:7], v10 offset0:4 offset1:5
	ds_read2st64_b32 v[8:9], v10 offset0:6 offset1:7
	s_cmp_gt_i32 s47, 1
	v_cndmask_b32_e64 v0, 0, v2, s[22:23]
	v_add_f32_e32 v1, v3, v0
	s_cselect_b64 s[24:25], -1, 0
	s_cmp_gt_i32 s47, 2
	v_cndmask_b32_e64 v0, v0, v1, s[24:25]
	s_waitcnt lgkmcnt(2)
	v_add_f32_e32 v1, v4, v0
	s_cselect_b64 s[18:19], -1, 0
	s_cmp_gt_i32 s47, 3
	v_cndmask_b32_e64 v0, v0, v1, s[18:19]
	v_add_f32_e32 v1, v5, v0
	s_cselect_b64 s[20:21], -1, 0
	s_cmp_gt_i32 s47, 4
	v_cndmask_b32_e64 v0, v0, v1, s[20:21]
	s_waitcnt lgkmcnt(1)
	v_add_f32_e32 v1, v6, v0
	s_cselect_b64 s[14:15], -1, 0
	s_cmp_gt_i32 s47, 5
	v_cndmask_b32_e64 v0, v0, v1, s[14:15]
	v_add_f32_e32 v1, v7, v0
	s_cselect_b64 s[16:17], -1, 0
	v_add_f32_e32 v2, v2, v3
	s_cmp_gt_i32 s47, 6
	v_cndmask_b32_e64 v0, v0, v1, s[16:17]
	v_add_f32_e32 v2, v2, v4
	s_waitcnt lgkmcnt(0)
	v_add_f32_e32 v1, v8, v0
	s_cselect_b64 s[10:11], -1, 0
	v_add_f32_e32 v2, v2, v5
	s_cmp_gt_i32 s47, 7
	v_cndmask_b32_e64 v11, v0, v1, s[10:11]
	v_add_f32_e32 v2, v2, v6
	v_add_f32_e32 v12, v9, v11
	s_cselect_b64 s[12:13], -1, 0
	v_add_f32_e32 v2, v2, v7
	v_add_f32_e32 v2, v2, v8
	v_cndmask_b32_e64 v7, v11, v12, s[12:13]
	s_movk_i32 s5, 0x8c
	v_mov_b32_e32 v3, v34
	v_mov_b32_e32 v6, v9
	v_mad_u32_u24 v4, v75, s5, v10
	v_add_f32_e32 v8, v20, v7
	v_add_f32_e32 v10, v30, v7
	v_pk_add_f32 v[2:3], v[2:3], v[6:7]
	v_add_f32_e32 v9, v32, v7
	v_sub_f32_e32 v6, v2, v8
	v_sub_f32_e32 v8, v2, v10
	v_sub_f32_e32 v9, v2, v9
	v_sub_f32_e32 v3, v2, v3
	v_mul_f32_e32 v6, 0x3fb8aa3b, v6
	v_mul_f32_e32 v8, 0x3fb8aa3b, v8
	v_mul_f32_e32 v9, 0x3fb8aa3b, v9
	v_mul_f32_e32 v3, 0x3fb8aa3b, v3
	v_add_f32_e32 v10, v25, v7
	v_exp_f32_e32 v6, v6
	v_exp_f32_e32 v8, v8
	v_exp_f32_e32 v9, v9
	v_exp_f32_e32 v3, v3
	v_sub_f32_e32 v10, v2, v10
	v_mul_f32_e32 v10, 0x3fb8aa3b, v10
	v_exp_f32_e32 v10, v10
	v_mul_f32_e32 v6, v93, v6
	v_mul_f32_e32 v8, v90, v8
	v_mul_f32_e32 v9, v100, v9
	v_mul_f32_e32 v3, v99, v3
	v_cvt_pk_bf16_f32 v6, v6, v145
	v_cvt_pk_bf16_f32 v8, v8, v145
	v_cvt_pk_bf16_f32 v9, v9, v145
	v_cvt_pk_bf16_f32 v3, v3, v145
	s_mov_b32 s5, 0x5040100
	v_perm_b32 v9, v3, v9, s5
	v_add_f32_e32 v3, v23, v7
	v_perm_b32 v8, v8, v6, s5
	v_mul_f32_e32 v6, v102, v10
	v_add_f32_e32 v10, v27, v7
	v_add_f32_e32 v7, v19, v7
	v_sub_f32_e32 v3, v2, v3
	v_sub_f32_e32 v7, v2, v7
	v_mul_f32_e32 v3, 0x3fb8aa3b, v3
	v_sub_f32_e32 v10, v2, v10
	v_mul_f32_e32 v7, 0x3fb8aa3b, v7
	v_exp_f32_e32 v3, v3
	v_mul_f32_e32 v10, 0x3fb8aa3b, v10
	v_exp_f32_e32 v7, v7
	v_exp_f32_e32 v10, v10
	v_mul_f32_e32 v3, v104, v3
	v_add_u32_e32 v5, s0, v4
	v_mul_f32_e32 v7, v105, v7
	v_cvt_pk_bf16_f32 v3, v3, v145
	v_cvt_pk_bf16_f32 v6, v6, v145
	v_mul_f32_e32 v10, v106, v10
	v_cvt_pk_bf16_f32 v7, v7, v145
	v_cvt_pk_bf16_f32 v10, v10, v145
	v_perm_b32 v6, v6, v3, s5
	v_perm_b32 v7, v7, v10, s5
	v_add_u32_e32 v3, 0x3000, v5
	v_lshl_add_u64 v[0:1], s[28:29], 0, v[144:145]
	s_mov_b64 s[8:9], 0x380000
	ds_write2_b64 v3, v[8:9], v[6:7] offset0:128 offset1:129
	v_cndmask_b32_e64 v3, 0, 1, s[30:31]
	s_movk_i32 s27, 0x90
	s_cmp_gt_u32 s48, 63
	v_lshl_add_u64 v[0:1], v[0:1], 0, s[8:9]
	v_cmp_ne_u32_e64 s[8:9], 1, v3
	s_cbranch_scc1 .LBB0_668
	v_mul_f32_e32 v2, 0x3fb8aa3b, v2
	v_exp_f32_e32 v2, v2
	s_movk_i32 s5, 0xff74
	v_mad_i32_i24 v3, v75, s5, v4
	s_and_b64 vcc, exec, s[8:9]
	ds_write_b32 v3, v2 offset:2048
	s_cbranch_vccnz .LBB0_668
	s_ashr_i32 s5, s4, 31
	s_lshl_b64 s[30:31], s[4:5], 8
	v_lshl_add_u64 v[4:5], v[0:1], 0, s[30:31]
	global_store_dword v[4:5], v2, off

; #define LAS __attribute__((address_space(3)))
; template <bool FINAL>
; DI void gla_unit(KA a, int l, int item, LAS unsigned char* lds) {
;     ...
;         float run0 = 0.f, run1 = 0.f;
; #pragma unroll
;         for (int jj = 0; jj < 8; ++jj) {
;             const int t = 8 * tg + jj;
;             float ga = 0.f, gb = 0.f;
;             if (t < nvalid) {
;                 const u32x4* lp = (const u32x4*)(U + (size_t)(row0 + t) * UN + U_LR);
;                 float lr[16]; unpack8(lp[0], lr); unpack8(lp[1], lr + 8);
;                 float za = bg[0], zb = bg[1];
; #pragma unroll
;                 for (int e = 0; e < 16; ++e) { za += wg[0][e] * lr[e]; zb += wg[1][e] * lr[e]; }
;                 ga = (fminf(za, 0.f) - __logf(1.f + __expf(-fabsf(za)))) * (1.f / 16.f);
;                 gb = (fminf(zb, 0.f) - __logf(1.f + __expf(-fabsf(zb)))) * (1.f / 16.f);
;             }
;             run0 += ga; run1 += gb; bl[0][jj] = run0; bl[1][jj] = run1;
;         }
;         ((LAS float*)(lds + GL_GSUM))[tg * 64 + dk] = run0;
.Lm3_nu1:
	v_mov_b32_e32 v80, v109
	s_waitcnt vmcnt(9)
	v_pk_add_f32 v[106:107], v[86:87], v[80:81]
	v_mov_b32_e32 v80, v87
	s_waitcnt vmcnt(1)
	v_readlane_b32 s82, v254, 0
	s_sub_i32 s72, s62, 0x188
	s_cmpk_lt_i32 s82, 8
	s_cbranch_scc1 .Lwm3_end
	s_cmpk_lt_i32 s82, 0x88
	s_cbranch_scc0 .Lwm3_c
	s_cmpk_lt_i32 s72, 0x88
	s_cbranch_scc1 .Lwm3_b128
	s_cmpk_lt_i32 s72, 0x108
	s_cbranch_scc0 .Lwm3_end
	s_cmpk_lt_i32 s82, 48
	s_cbranch_scc0 .Lwm3_end

; DI UnitInfo decode_unit(int unit) {
;     UnitInfo u;
;     if (unit < NUNIT_P) { u.prompt = 1; u.b = unit / NCH; u.c = unit - u.b * NCH; u.s = 0; const int tau0 = u.c == 0 ? 0 : NMETA + 64 * (u.c - 1); u.nvalid = u.c == 0 ? NMETA : 64; u.row0 = u.b * LP + tau0; }
;     else { u.prompt = 0; u.s = unit - NUNIT_P; u.b = 0; u.c = 0; u.row0 = MP + LS * u.s; u.nvalid = LS; }
;     return u;
.Lwm3_dec:
	s_add_u32 s84, s28, 0x5000000
	s_addc_u32 s85, s29, 0
	s_lshl_b32 s86, s43, 3
	s_lshr_b32 s73, s72, 1
	s_and_b32 s74, s72, 1
	s_cmpk_lt_u32 s73, 0x108
	s_cbranch_scc0 .Lwm3_samp
	s_mul_i32 s75, s73, 0xf83f
	s_lshr_b32 s75, s75, 21
	s_mul_i32 s76, s75, 0xffffffdf
	s_add_i32 s76, s76, s73
	s_lshl_b32 s77, s76, 6
	s_sub_i32 s77, s77, 48
	s_cmp_eq_u32 s76, 0
	s_cselect_b32 s77, 0, s77
	s_cselect_b32 s78, 15, 63
	s_cselect_b32 s79, 0, 1
	s_mulk_i32 s75, 0x810
	s_add_i32 s77, s77, s75
	s_branch .Lwm3_go

; DI float bf2f(unsigned v) { return __uint_as_float(v << 16); }
; template <bool FINAL>
; DI void gla_unit(KA a, int l, int item, LAS unsigned char* lds) {
;     ...
;     for (int hh = 0; hh < 2; ++hh) {
;         const int hd = 2 * hp + hh;
; #pragma unroll
;         for (int jj = 0; jj < 8; ++jj) {
;             const int t = 8 * tg + jj; kraw[hh][jj] = 0u; qraw[hh][jj] = 0u;
;             if (t < nvalid) { kraw[hh][jj] = U[(size_t)(row0 + t) * UN + U_K + hd * 64 + dk]; if (FINAL) qraw[hh][jj] = U[(size_t)(row0 + t) * UN + U_Q + hd * 64 + dk]; }
;         }
;         v0[hh] = (u32x4){0u, 0u, 0u, 0u}; v1[hh] = v0[hh]; g0[hh] = v0[hh]; g1[hh] = v0[hh];
;         if (vj < nvalid) {
;             const u32x4* vp = (const u32x4*)(U + (size_t)(row0 + vj) * UN + U_V + hd * 128 + vdvc); v0[hh] = vp[0]; v1[hh] = vp[1];
;             if (FINAL) { const u32x4* gp = (const u32x4*)(U + (size_t)(row0 + vj) * UN + U_GO + hd * 128 + vdvc); g0[hh] = gp[0]; g1[hh] = gp[1]; }
;         }
;         S0[hh] = nullptr;
;         if (!u.prompt) S0[hh] = a->in[4] + (size_t)((l * NSB + u.s) * 4 + hd) * 8192;
;         if (FINAL) {
;             const bf16_t* Sb = (u.prompt && u.c > 0) ? (const bf16_t*)(a->ws + WS_SB) + (size_t)(unit * 4 + hd) * 8192 : nullptr;
; #pragma unroll
;             for (int it = 0; it < 4; ++it) {
;                 const int idx = it * 512 + tid; sv[hh][it] = (f32x4){0.f, 0.f, 0.f, 0.f};
;                 if (S0[hh]) sv[hh][it] = *(const f32x4*)(S0[hh] + (idx >> 5) * 128 + (idx & 31) * 4);
;                 else if (Sb) { const u32x2 v = *(const u32x2*)(Sb + (idx >> 5) * 128 + (idx & 31) * 4); sv[hh][it] = (f32x4){bf2f(v.x & 0xffffu), __uint_as_float(v.x & 0xffff0000u), bf2f(v.y & 0xffffu), __uint_as_float(v.y & 0xffff0000u)}; }
;             }
.Lwm3_go:
	v_and_b32_e32 v187, 15, v85
	v_lshrrev_b32_e32 v188, 4, v85
	v_add_u32_e32 v188, s86, v188
	s_lshl_b32 s80, s74, 8
	s_lshl_b32 s81, s74, 9
	v_lshlrev_b32_e32 v189, 7, v187
	s_add_i32 s75, s80, 0xa00
	v_mov_b32_e32 v190, s75
	s_add_i32 s75, s80, 0x700
	v_mov_b32_e32 v191, s75
	v_cmp_gt_u32_e32 vcc, 2, v187
	s_nop 1
	v_cndmask_b32_e32 v190, v191, v190, vcc
	s_add_i32 s75, s81, 0xa00
	v_mov_b32_e32 v191, s75
	v_cmp_gt_u32_e32 vcc, 4, v187
	s_nop 1
	v_cndmask_b32_e32 v190, v191, v190, vcc
	s_add_i32 s75, s81, 0xc00
	v_mov_b32_e32 v191, s75
	v_cmp_gt_u32_e32 vcc, 8, v187
	s_nop 1
	v_cndmask_b32_e32 v190, v191, v190, vcc
	v_add_u32_e32 v189, v189, v190
	v_mov_b32_e32 v191, 0x1400
	v_cmp_gt_u32_e32 vcc, 12, v187
	s_nop 1
	v_cndmask_b32_e32 v189, v191, v189, vcc
	v_min_u32_e32 v194, s78, v188
	v_add_u32_e32 v194, s77, v194
	v_mul_u32_u24_e32 v194, 0x1600, v194
	v_add_u32_e32 v194, v194, v189
	global_load_dword v195, v194, s[84:85]
	v_add_u32_e32 v188, 4, v188
	v_min_u32_e32 v194, s78, v188
	v_add_u32_e32 v194, s77, v194
	v_mul_u32_u24_e32 v194, 0x1600, v194
	v_add_u32_e32 v194, v194, v189
	global_load_dword v195, v194, s[84:85]
	s_cmp_eq_u32 s79, 0
	s_cbranch_scc1 .Lwm3_end
	s_lshl_b32 s75, s73, 2
	s_lshl_b32 s76, s74, 1
	s_add_i32 s75, s75, s76
	s_lshl_b32 s75, s75, 14
	s_add_i32 s75, s75, 0x8200000
	s_lshl_b32 s76, s86, 9
	s_add_i32 s75, s75, s76
	v_and_b32_e32 v194, 31, v85
	v_lshlrev_b32_e32 v194, 7, v194
	v_add_u32_e32 v194, s75, v194
	global_load_dword v195, v194, s[84:85]
; #define LAS __attribute__((address_space(3)))
; DI bf16_t f2bf(float f) { return (bf16_t)(cvt_pk(f, 0.f) & 0xffffu); }
; template <bool FINAL>
; DI void gla_unit(KA a, int l, int item, LAS unsigned char* lds) {
;     ...
;         float run0 = 0.f, run1 = 0.f;
; #pragma unroll
;         for (int jj = 0; jj < 8; ++jj) {
;             const int t = 8 * tg + jj;
;             float ga = 0.f, gb = 0.f;
;             if (t < nvalid) {
;                 const u32x4* lp = (const u32x4*)(U + (size_t)(row0 + t) * UN + U_LR);
;                 float lr[16]; unpack8(lp[0], lr); unpack8(lp[1], lr + 8);
;                 float za = bg[0], zb = bg[1];
; #pragma unroll
;                 for (int e = 0; e < 16; ++e) { za += wg[0][e] * lr[e]; zb += wg[1][e] * lr[e]; }
;                 ga = (fminf(za, 0.f) - __logf(1.f + __expf(-fabsf(za)))) * (1.f / 16.f);
;                 gb = (fminf(zb, 0.f) - __logf(1.f + __expf(-fabsf(zb)))) * (1.f / 16.f);
;             }
;             run0 += ga; run1 += gb; bl[0][jj] = run0; bl[1][jj] = run1;
;         }
;         ((LAS float*)(lds + GL_GSUM))[tg * 64 + dk] = run0;
;         ((LAS float*)(lds + GL_HEAD + GL_GSUM))[tg * 64 + dk] = run1;
;     }
; #pragma unroll
;     for (int hh = 0; hh < 2; ++hh) {
;         LAS bf16_t* vT = (LAS bf16_t*)(lds + hh * GL_HEAD + GL_VT); LAS bf16_t* sT = (LAS bf16_t*)(lds + hh * GL_HEAD + GL_ST);
;         {
;             const unsigned vv[8] = {v0[hh].x, v0[hh].y, v0[hh].z, v0[hh].w, v1[hh].x, v1[hh].y, v1[hh].z, v1[hh].w};
;             const int col = ((((vj >> 3) ^ ((vdvc >> 4) & 7)) << 3) | (vj & 7));
; #pragma unroll
;             for (int e = 0; e < 8; ++e) { vT[(vdvc + 2 * e) * 72 + col] = (bf16_t)(vv[e] & 0xffffu); vT[(vdvc + 2 * e + 1) * 72 + col] = (bf16_t)(vv[e] >> 16); }
;         }
;         if (FINAL) {
; #pragma unroll
;             for (int it = 0; it < 4; ++it) {
;                 const int idx = it * 512 + tid, dkk = idx >> 5, dv4 = (idx & 31) * 4;
;                 const int col = ((((dkk >> 3) ^ ((dv4 >> 4) & 7)) << 3) | (dkk & 7));
;                 sT[(dv4 + 0) * 72 + col] = f2bf(sv[hh][it].x); sT[(dv4 + 1) * 72 + col] = f2bf(sv[hh][it].y); sT[(dv4 + 2) * 72 + col] = f2bf(sv[hh][it].z); sT[(dv4 + 3) * 72 + col] = f2bf(sv[hh][it].w);
;             }
;         }
;     }
.Lwm3_end:
	v_pk_add_f32 v[94:95], v[80:81], v[108:109]
	v_mov_b32_e32 v80, v113
	v_pk_add_f32 v[104:105], v[106:107], v[80:81]
	v_mov_b32_e32 v80, v111
	v_pk_add_f32 v[92:93], v[94:95], v[112:113]
	v_pk_add_f32 v[102:103], v[104:105], v[80:81]
	v_mov_b32_e32 v80, v117
	v_pk_add_f32 v[90:91], v[92:93], v[110:111]
	v_pk_add_f32 v[100:101], v[102:103], v[80:81]
	v_mov_b32_e32 v80, v115
	v_pk_add_f32 v[88:89], v[90:91], v[116:117]
	v_pk_add_f32 v[98:99], v[100:101], v[80:81]
	v_mov_b32_e32 v80, v121
	s_and_b32 s0, s44, 0x3fffffc0
	v_pk_add_f32 v[82:83], v[88:89], v[114:115]
	v_pk_add_f32 v[96:97], v[98:99], v[80:81]
	v_or_b32_e32 v89, s0, v85
	v_pk_add_f32 v[80:81], v[82:83], v[120:121]
	v_add_f32_e32 v83, v96, v119
	v_lshl_add_u32 v89, v89, 2, 0
	v_add_f32_e32 v81, v80, v118
	ds_write_b32 v89, v83
	v_add_u32_e32 v89, 0x10c00, v89
	ds_write_b32 v89, v81
	v_ashrrev_i32_e32 v89, 6, v123
	v_lshrrev_b32_e32 v97, 2, v123
	v_bitop3_b32 v89, v89, v123, 7 bitop3:0x78
	v_and_b32_e32 v97, 14, v97
	v_mul_u32_u24_e32 v95, 0x90, v167
	v_lshl_or_b32 v89, v89, 4, v97
	v_add3_u32 v95, 0, v95, v89
	v_lshrrev_b32_e32 v91, 4, v169
	v_ashrrev_i32_e32 v93, 8, v123
	ds_write_b16 v95, v4 offset:22528
	ds_write_b16_d16_hi v95, v4 offset:22672
	ds_write_b16 v95, v5 offset:22816
	ds_write_b16_d16_hi v95, v5 offset:22960
	ds_write_b16 v95, v6 offset:23104
	ds_write_b16_d16_hi v95, v6 offset:23248
	ds_write_b16 v95, v7 offset:23392
	ds_write_b16_d16_hi v95, v7 offset:23536
	ds_write_b16 v95, v0 offset:23680
	ds_write_b16_d16_hi v95, v0 offset:23824
	ds_write_b16 v95, v1 offset:23968
	ds_write_b16_d16_hi v95, v1 offset:24112
	ds_write_b16 v95, v2 offset:24256
	ds_write_b16_d16_hi v95, v2 offset:24400
	ds_write_b16 v95, v3 offset:24544
	ds_write_b16_d16_hi v95, v3 offset:24688
	v_lshrrev_b32_e32 v95, 4, v123
	v_bitop3_b32 v93, v91, v93, 7 bitop3:0x6c
	s_movk_i32 s0, 0x90
	v_and_b32_e32 v95, 14, v95
	v_mad_u32_u24 v3, v168, s0, 0
	v_lshl_or_b32 v93, v93, 4, v95
	v_cvt_pk_bf16_f32 v8, v8, v145
	v_add_u32_e32 v97, v3, v93
	ds_write_b16 v97, v8 offset:40960
	v_cvt_pk_bf16_f32 v8, v9, v145
	ds_write_b16 v97, v8 offset:41104
	v_cvt_pk_bf16_f32 v8, v10, v145
	ds_write_b16 v97, v8 offset:41248
	v_cvt_pk_bf16_f32 v8, v11, v145
	ds_write_b16 v97, v8 offset:41392
	v_ashrrev_i32_e32 v8, 8, v170
	v_bitop3_b32 v8, v91, v8, 7 bitop3:0x6c
	v_lshl_or_b32 v8, v8, 4, v95
	v_cvt_pk_bf16_f32 v9, v12, v145
	v_add_u32_e32 v10, v3, v8
	ds_write_b16 v10, v9 offset:40960
	v_cvt_pk_bf16_f32 v9, v13, v145
	ds_write_b16 v10, v9 offset:41104
	v_cvt_pk_bf16_f32 v9, v14, v145
	ds_write_b16 v10, v9 offset:41248
	v_cvt_pk_bf16_f32 v9, v15, v145
	ds_write_b16 v10, v9 offset:41392
	v_ashrrev_i32_e32 v9, 8, v171
	v_bitop3_b32 v9, v91, v9, 7 bitop3:0x6c
	v_lshl_or_b32 v9, v9, 4, v95
	v_cvt_pk_bf16_f32 v10, v16, v145
	v_add_u32_e32 v11, v3, v9
	ds_write_b16 v11, v10 offset:40960
	v_cvt_pk_bf16_f32 v10, v17, v145
	ds_write_b16 v11, v10 offset:41104
	v_cvt_pk_bf16_f32 v10, v18, v145
	ds_write_b16 v11, v10 offset:41248
	v_cvt_pk_bf16_f32 v10, v19, v145
	ds_write_b16 v11, v10 offset:41392
	v_ashrrev_i32_e32 v10, 8, v172
	v_bitop3_b32 v10, v91, v10, 7 bitop3:0x6c
	v_lshl_or_b32 v10, v10, 4, v95
	v_cvt_pk_bf16_f32 v11, v20, v145
	v_add_u32_e32 v3, v3, v10
	ds_write_b16 v3, v11 offset:40960
	v_cvt_pk_bf16_f32 v11, v21, v145
	ds_write_b16 v3, v11 offset:41104
	v_cvt_pk_bf16_f32 v11, v22, v145
	v_readlane_b32 s2, v254, 47
	ds_write_b16 v3, v11 offset:41248
	v_cvt_pk_bf16_f32 v11, v23, v145
	ds_write_b16 v3, v11 offset:41392
	v_add_u32_e32 v3, s2, v89
	v_mad_u32_u24 v4, v167, s0, v223
	v_mad_u32_u24 v11, v167, s0, v3
	v_mad_u32_u24 v5, v167, s0, v224
	ds_write_b16 v11, v28
	ds_write_b16_d16_hi v11, v28 offset:144
	v_add_u32_e32 v11, v3, v4
	v_add3_u32 v4, s2, v4, v89
	ds_write_b16_d16_hi v4, v29 offset:144
	v_add_u32_e32 v4, v3, v5
	v_mad_u32_u24 v6, v167, s0, v225
	ds_write_b16 v4, v30
	v_add3_u32 v4, s2, v5, v89
	ds_write_b16_d16_hi v4, v30 offset:144
	v_add_u32_e32 v4, v3, v6
	v_mad_u32_u24 v7, v167, s0, v226
	ds_write_b16 v4, v31
	v_add3_u32 v4, s2, v6, v89
	ds_write_b16_d16_hi v4, v31 offset:144
	v_add_u32_e32 v4, v3, v7
	v_mad_u32_u24 v0, v167, s0, v227
	ds_write_b16 v4, v24
	v_add3_u32 v4, s2, v7, v89
	v_mad_u32_u24 v1, v167, s0, v228
	ds_write_b16_d16_hi v4, v24 offset:144
	v_add_u32_e32 v4, v3, v0
	v_add3_u32 v0, s2, v0, v89
	ds_write_b16_d16_hi v0, v25 offset:144
	v_add_u32_e32 v0, v3, v1
	v_mad_u32_u24 v2, v167, s0, v229
	ds_write_b16 v0, v26
	v_add3_u32 v0, s2, v1, v89
	ds_write_b16_d16_hi v0, v26 offset:144
	v_add_u32_e32 v0, v3, v2
	ds_write_b16 v0, v27
	v_add3_u32 v0, s2, v2, v89
	v_readlane_b32 s2, v254, 48
	ds_write_b16_d16_hi v0, v27 offset:144
	v_cvt_pk_bf16_f32 v1, v64, v145
	ds_write_b16 v11, v29
	v_mov_b32_e32 v0, s2
	v_mad_u32_u24 v0, v168, s0, v0
	v_add_u32_e32 v2, v0, v93
	ds_write_b16 v4, v25
	ds_write_b16 v2, v1
	v_cvt_pk_bf16_f32 v1, v65, v145
	ds_write_b16 v2, v1 offset:144
	v_cvt_pk_bf16_f32 v1, v66, v145
	ds_write_b16 v2, v1 offset:288
	v_cvt_pk_bf16_f32 v1, v67, v145
	ds_write_b16 v2, v1 offset:432
	v_cvt_pk_bf16_f32 v1, v68, v145
	v_add_u32_e32 v2, v0, v8
	ds_write_b16 v2, v1
	v_cvt_pk_bf16_f32 v1, v69, v145
	ds_write_b16 v2, v1 offset:144
	v_cvt_pk_bf16_f32 v1, v70, v145
	ds_write_b16 v2, v1 offset:288
	v_cvt_pk_bf16_f32 v1, v71, v145
	ds_write_b16 v2, v1 offset:432
	v_cvt_pk_bf16_f32 v1, v72, v145
	v_add_u32_e32 v2, v0, v9
	ds_write_b16 v2, v1
	v_cvt_pk_bf16_f32 v1, v73, v145
	ds_write_b16 v2, v1 offset:144
	v_cvt_pk_bf16_f32 v1, v74, v145
	ds_write_b16 v2, v1 offset:288
	v_cvt_pk_bf16_f32 v1, v75, v145
	ds_write_b16 v2, v1 offset:432
	v_cvt_pk_bf16_f32 v1, v76, v145
	v_add_u32_e32 v0, v0, v10
	ds_write_b16 v0, v1
	v_cvt_pk_bf16_f32 v1, v77, v145
	ds_write_b16 v0, v1 offset:144
	v_cvt_pk_bf16_f32 v1, v78, v145
	ds_write_b16 v0, v1 offset:288
	v_cvt_pk_bf16_f32 v1, v79, v145
	ds_write_b16 v0, v1 offset:432
	s_waitcnt lgkmcnt(0)
	s_barrier
	s_cmp_gt_i32 s43, 0
	s_cselect_b64 s[18:19], -1, 0
	s_cmp_lt_i32 s43, 1
	v_lshl_add_u32 v0, v85, 2, 0
	s_cbranch_scc1 .LBB0_963
	ds_read_b32 v1, v0
	s_waitcnt lgkmcnt(0)
	v_add_f32_e32 v2, 0, v1
	s_cmp_gt_i32 s43, 1
	s_cselect_b64 s[2:3], -1, 0
	s_cmp_lt_i32 s43, 2
	s_cbranch_scc1 .LBB0_904

; #define LAS __attribute__((address_space(3)))
; DI int opaque_tid() { int t = threadIdx.x; asm volatile("" : "+v"(t)); return t; }
; template <bool FINAL>
; DI void lru_unit(KA a, int l, int unit, LAS unsigned char* lds) {
;     const UnitInfo u = decode_unit(unit);
;     const int tid = opaque_tid(), lane = tid & 63, w = __builtin_amdgcn_readfirstlane(tid >> 6), r = lane & 31, h = lane >> 5;
;     const bf16_t* U = (const bf16_t*)(a->ws + WS_HU);
;     LAS bf16_t* xc = (LAS bf16_t*)lds + w * (64 * 72);
;     LAS unsigned char* wsc = lds + 73728 + w * 8192;
;     LAS bf16_t* xr = (LAS bf16_t*)wsc;
;     const int row0 = u.row0, nvalid = u.nvalid;
.LBB0_958:
	s_or_b64 exec, exec, s[6:7]
	s_ashr_i32 s10, s8, 6
	v_mov_b32_e32 v200, s4
	v_mov_b32_e32 v201, s5
	v_mov_b32_e32 v202, s4
	v_mov_b32_e32 v203, s5
	v_mov_b32_e32 v204, s4
	v_mov_b32_e32 v205, s5
	v_readlane_b32 s82, v254, 0
	s_add_i32 s83, s62, 0x100
	s_cmp_eq_u32 s62, s82
	s_cselect_b32 s84, 1, 0
	s_cmpk_lt_i32 s83, 0x188
	s_cselect_b32 s85, 1, 0
	s_and_b32 s84, s84, s85
	s_cmp_lg_u32 s84, 0
	s_cbranch_scc1 .Lwlr_end
	s_cmpk_lt_i32 s82, 0x88
	s_cselect_b32 s83, 0, 0xa8
	s_add_i32 s72, s82, s83
	s_lshl_b32 s86, s10, 3
	v_and_b32_e32 v206, 63, v35
	s_lshr_b32 s73, s72, 1
	s_and_b32 s74, s72, 1
	s_cmpk_lt_u32 s73, 0x108
	s_cbranch_scc0 .Lwlr_samp
	s_mul_i32 s75, s73, 0xf83f
	s_lshr_b32 s75, s75, 21
	s_mul_i32 s76, s75, 0xffffffdf
	s_add_i32 s76, s76, s73
	s_lshl_b32 s77, s76, 6
	s_sub_i32 s77, s77, 48
	s_cmp_eq_u32 s76, 0
	s_cselect_b32 s77, 0, s77
	s_cselect_b32 s78, 15, 63
	s_cselect_b32 s79, 0, 1
	s_mulk_i32 s75, 0x810
	s_add_i32 s77, s77, s75
	s_branch .Lwlr_go

; DI float bf2f(unsigned v) { return __uint_as_float(v << 16); }
; template <bool FINAL>
; DI void gla_unit(KA a, int l, int item, LAS unsigned char* lds) {
;     ...
;     for (int hh = 0; hh < 2; ++hh) {
;         const int hd = 2 * hp + hh;
; #pragma unroll
;         for (int jj = 0; jj < 8; ++jj) {
;             const int t = 8 * tg + jj; kraw[hh][jj] = 0u; qraw[hh][jj] = 0u;
;             if (t < nvalid) { kraw[hh][jj] = U[(size_t)(row0 + t) * UN + U_K + hd * 64 + dk]; if (FINAL) qraw[hh][jj] = U[(size_t)(row0 + t) * UN + U_Q + hd * 64 + dk]; }
;         }
;         v0[hh] = (u32x4){0u, 0u, 0u, 0u}; v1[hh] = v0[hh]; g0[hh] = v0[hh]; g1[hh] = v0[hh];
;         if (vj < nvalid) {
;             const u32x4* vp = (const u32x4*)(U + (size_t)(row0 + vj) * UN + U_V + hd * 128 + vdvc); v0[hh] = vp[0]; v1[hh] = vp[1];
;             if (FINAL) { const u32x4* gp = (const u32x4*)(U + (size_t)(row0 + vj) * UN + U_GO + hd * 128 + vdvc); g0[hh] = gp[0]; g1[hh] = gp[1]; }
;         }
;         S0[hh] = nullptr;
;         if (!u.prompt) S0[hh] = a->in[4] + (size_t)((l * NSB + u.s) * 4 + hd) * 8192;
;         if (FINAL) {
;             const bf16_t* Sb = (u.prompt && u.c > 0) ? (const bf16_t*)(a->ws + WS_SB) + (size_t)(unit * 4 + hd) * 8192 : nullptr;
; #pragma unroll
;             for (int it = 0; it < 4; ++it) {
;                 const int idx = it * 512 + tid; sv[hh][it] = (f32x4){0.f, 0.f, 0.f, 0.f};
;                 if (S0[hh]) sv[hh][it] = *(const f32x4*)(S0[hh] + (idx >> 5) * 128 + (idx & 31) * 4);
;                 else if (Sb) { const u32x2 v = *(const u32x2*)(Sb + (idx >> 5) * 128 + (idx & 31) * 4); sv[hh][it] = (f32x4){bf2f(v.x & 0xffffu), __uint_as_float(v.x & 0xffff0000u), bf2f(v.y & 0xffffu), __uint_as_float(v.y & 0xffff0000u)}; }
;             }
.Lwlr_go:
	v_and_b32_e32 v207, 15, v206
	v_lshrrev_b32_e32 v208, 4, v206
	v_add_u32_e32 v208, s86, v208
	s_lshl_b32 s80, s74, 8
	s_lshl_b32 s81, s74, 9
	v_lshlrev_b32_e32 v209, 7, v207
	s_add_i32 s75, s80, 0xa00
	v_mov_b32_e32 v210, s75
	s_add_i32 s75, s80, 0x700
	v_mov_b32_e32 v211, s75
	v_cmp_gt_u32_e32 vcc, 2, v207
	s_nop 1
	v_cndmask_b32_e32 v210, v211, v210, vcc
	s_add_i32 s75, s81, 0xa00
	v_mov_b32_e32 v211, s75
	v_cmp_gt_u32_e32 vcc, 4, v207
	s_nop 1
	v_cndmask_b32_e32 v210, v211, v210, vcc
	s_add_i32 s75, s81, 0xc00
	v_mov_b32_e32 v211, s75
	v_cmp_gt_u32_e32 vcc, 8, v207
	s_nop 1
	v_cndmask_b32_e32 v210, v211, v210, vcc
	v_add_u32_e32 v209, v209, v210
	v_mov_b32_e32 v211, 0x1400
	v_cmp_gt_u32_e32 vcc, 12, v207
	s_nop 1
	v_cndmask_b32_e32 v209, v211, v209, vcc
	v_min_u32_e32 v199, s78, v208
	v_add_u32_e32 v199, s77, v199
	v_mul_u32_u24_e32 v199, 0x1600, v199
	v_add_u32_e32 v199, v199, v209
	v_mov_b32_e32 v201, s5
	v_add_co_u32_e32 v200, vcc, s4, v199
	s_nop 1
	v_addc_co_u32_e32 v201, vcc, 0, v201, vcc
	v_add_u32_e32 v208, 4, v208
	v_min_u32_e32 v199, s78, v208
	v_add_u32_e32 v199, s77, v199
	v_mul_u32_u24_e32 v199, 0x1600, v199
	v_add_u32_e32 v199, v199, v209
	v_mov_b32_e32 v203, s5
	v_add_co_u32_e32 v202, vcc, s4, v199
	s_nop 1
	v_addc_co_u32_e32 v203, vcc, 0, v203, vcc
	s_cmp_eq_u32 s79, 0
	s_cbranch_scc1 .Lwlr_end
	s_lshl_b32 s75, s73, 2
	s_lshl_b32 s76, s74, 1
	s_add_i32 s75, s75, s76
	s_lshl_b32 s75, s75, 14
	s_add_i32 s75, s75, 0x8200000
	s_lshl_b32 s76, s86, 9
	s_add_i32 s75, s75, s76
	v_and_b32_e32 v199, 31, v206
	v_lshlrev_b32_e32 v199, 7, v199
	v_add_u32_e32 v199, s75, v199
	v_mov_b32_e32 v205, s5
	v_add_co_u32_e32 v204, vcc, s4, v199
	s_nop 1
	v_addc_co_u32_e32 v205, vcc, 0, v205, vcc

; DI float bf2f(unsigned v) { return __uint_as_float(v << 16); }
; DI float sigmoidf_(float x) { return rcpf(1.f + __expf(-x)); }
; template <bool FINAL>
; DI void lru_unit(KA a, int l, int unit, LAS unsigned char* lds) {
;     ...
;         const int cl = 32 * nb + r, chn = 64 * w + cl;
;         const float ba_ = a->in[14][l * DLRU + chn], bx_ = a->in[16][l * DLRU + chn];
;         const float c8 = -8.f * log1pf(__expf(-a->in[17][l * DLRU + chn]));
;         float cin = 0.f;
;         if (FINAL && !u.prompt) cin = a->in[2][(size_t)(l * NSB + u.s) * DLRU + chn];
; #pragma unroll
;         for (int mb = 0; mb < 2; ++mb) {
;             float pp = 1.f, hh = 0.f;
; #pragma unroll
;             for (int i = 0; i < 16; ++i) {
;                 const int t = 32 * mb + 16 * h + i;
;                 const float rg = sigmoidf_(ar[mb][i] + ba_), ig = sigmoidf_(ai[mb][i] + bx_);
;                 const float la = c8 * rg;
;                 float av = __expf(la), mult = __builtin_amdgcn_sqrtf(fmaxf(1.f - av * av, 0.f));
;                 const float xcv = bf2f(xc[t * 72 + cl]);
.LBB0_1015:
	s_waitcnt vmcnt(0)
	global_load_dword v199, v[200:201], off
	global_load_dword v199, v[202:203], off
	global_load_dword v199, v[204:205], off
	v_mul_f32_e32 v178, 0xbfb8aa3b, v178
	v_exp_f32_e32 v178, v178
	s_mov_b32 s4, 0x3f2aaaab
	v_add_f32_e32 v48, v48, v177
	v_mul_f32_e32 v48, 0xbfb8aa3b, v48
	v_add_f32_e32 v182, 1.0, v178
	v_frexp_mant_f32_e32 v184, v182
	v_cvt_f64_f32_e32 v[180:181], v182
	v_add_f32_e32 v183, -1.0, v182
	v_frexp_exp_i32_f64_e32 v180, v[180:181]
	v_cmp_gt_f32_e32 vcc, s4, v184
	v_sub_f32_e32 v185, v183, v182
	v_sub_f32_e32 v183, v178, v183
	v_subbrev_co_u32_e32 v180, vcc, 0, v180, vcc
	v_add_f32_e32 v185, 1.0, v185
	v_sub_u32_e32 v181, 0, v180
	v_add_f32_e32 v183, v183, v185
	v_ldexp_f32 v182, v182, v181
	v_ldexp_f32 v181, v183, v181
	v_add_f32_e32 v183, -1.0, v182
	v_add_f32_e32 v186, 1.0, v182
	v_add_f32_e32 v184, 1.0, v183
	v_add_f32_e32 v187, -1.0, v186
	v_sub_f32_e32 v184, v182, v184
	v_sub_f32_e32 v182, v182, v187
	v_add_f32_e32 v184, v181, v184
	v_add_f32_e32 v181, v181, v182
	v_add_f32_e32 v182, v186, v181
	v_rcp_f32_e32 v187, v182
	v_add_f32_e32 v185, v183, v184
	v_sub_f32_e32 v183, v185, v183
	v_sub_f32_e32 v183, v184, v183
	v_sub_f32_e32 v184, v182, v186
	v_sub_f32_e32 v181, v181, v184
	v_mul_f32_e32 v184, v185, v187
	v_mul_f32_e32 v186, v182, v184
	v_fma_f32 v188, v184, v182, -v186
	v_fmac_f32_e32 v188, v184, v181
	v_add_f32_e32 v189, v186, v188
	v_sub_f32_e32 v190, v185, v189
	v_sub_f32_e32 v185, v185, v190
	v_sub_f32_e32 v186, v189, v186
	v_sub_f32_e32 v185, v185, v189
	v_add_f32_e32 v183, v183, v185
	v_sub_f32_e32 v185, v186, v188
	v_add_f32_e32 v183, v185, v183
	v_add_f32_e32 v185, v190, v183
	v_mul_f32_e32 v186, v187, v185
	v_mul_f32_e32 v188, v182, v186
	v_fma_f32 v182, v186, v182, -v188
	v_fmac_f32_e32 v182, v186, v181
	v_sub_f32_e32 v181, v190, v185
	v_add_f32_e32 v181, v183, v181
	v_add_f32_e32 v183, v188, v182
	v_sub_f32_e32 v189, v185, v183
	v_sub_f32_e32 v185, v185, v189
	v_sub_f32_e32 v188, v183, v188
	v_sub_f32_e32 v183, v185, v183
	v_add_f32_e32 v181, v181, v183
	v_sub_f32_e32 v182, v188, v182
	v_cvt_f32_i32_e32 v180, v180
	v_add_f32_e32 v181, v182, v181
	v_add_f32_e32 v182, v184, v186
	v_add_f32_e32 v181, v189, v181
	v_sub_f32_e32 v183, v182, v184
	v_mul_f32_e32 v181, v187, v181
	v_sub_f32_e32 v183, v186, v183
	v_add_f32_e32 v181, v183, v181
	v_mul_f32_e32 v186, 0x3f317218, v180
	s_mov_b32 s4, 0x3f317218
	v_add_f32_e32 v183, v182, v181
	v_fma_f32 v187, v180, s4, -v186
	v_mul_f32_e32 v184, v183, v183
	v_mov_b32_e32 v185, 0x3ecc95a3
	v_fmac_f32_e32 v187, 0xb102e308, v180
	v_sub_f32_e32 v180, v183, v182
	v_fmamk_f32 v185, v184, 0x3e9b6dac, v185
	v_sub_f32_e32 v180, v181, v180
	v_add_f32_e32 v181, v186, v187
	v_fmaak_f32 v185, v184, v185, 0x3f2aaada
	v_sub_f32_e32 v182, v181, v186
	v_ldexp_f32 v186, v183, 1
	v_mul_f32_e32 v183, v183, v184
	v_mul_f32_e32 v183, v183, v185
	v_add_f32_e32 v184, v186, v183
	v_sub_f32_e32 v185, v184, v186
	v_ldexp_f32 v180, v180, 1
	v_sub_f32_e32 v183, v183, v185
	v_add_f32_e32 v180, v180, v183
	v_add_f32_e32 v183, v184, v180
	v_sub_f32_e32 v184, v183, v184
	v_sub_f32_e32 v180, v180, v184
	v_add_f32_e32 v184, v181, v183
	v_sub_f32_e32 v185, v184, v181
	v_sub_f32_e32 v186, v184, v185
	v_sub_f32_e32 v182, v187, v182
	v_sub_f32_e32 v181, v181, v186
	v_sub_f32_e32 v183, v183, v185
	v_add_f32_e32 v181, v183, v181
	v_add_f32_e32 v183, v182, v180
	v_sub_f32_e32 v185, v183, v182
	v_sub_f32_e32 v186, v183, v185
	v_sub_f32_e32 v182, v182, v186
	v_sub_f32_e32 v180, v180, v185
	v_add_f32_e32 v181, v183, v181
	v_add_f32_e32 v180, v180, v182
	v_add_f32_e32 v182, v184, v181
	v_sub_f32_e32 v183, v182, v184
	v_exp_f32_e32 v48, v48
	v_sub_f32_e32 v181, v181, v183
	v_add_f32_e32 v180, v180, v181
	s_mov_b32 s4, 0x7f800000
	v_add_f32_e32 v180, v182, v180
	v_cmp_neq_f32_e32 vcc, s4, v178
	v_add_f32_e32 v48, 1.0, v48
	s_mov_b32 s4, 0x33800000
	v_cndmask_b32_e32 v180, v230, v180, vcc
	v_cmp_ngt_f32_e32 vcc, -1.0, v178
	v_rcp_f32_e32 v48, v48
	v_add_f32_e32 v49, v49, v177
	v_cndmask_b32_e32 v180, v231, v180, vcc
	v_cmp_neq_f32_e32 vcc, -1.0, v178
	v_mul_f32_e32 v49, 0xbfb8aa3b, v49
	v_exp_f32_e32 v49, v49
	v_cndmask_b32_e32 v180, v232, v180, vcc
	v_cmp_lt_f32_e64 vcc, |v178|, s4
	v_add_f32_e32 v32, v32, v176
	v_mul_f32_e32 v32, 0xbfb8aa3b, v32
	v_cndmask_b32_e32 v178, v180, v178, vcc
	v_mul_f32_e32 v178, 0xc1000000, v178
	v_mul_f32_e32 v48, v48, v178
	v_mul_f32_e32 v48, 0x3fb8aa3b, v48
	v_exp_f32_e32 v48, v48
	v_add_f32_e32 v49, 1.0, v49
	v_exp_f32_e32 v32, v32
	v_rcp_f32_e32 v49, v49
	v_fma_f32 v180, -v48, v48, 1.0
	v_add_f32_e32 v33, v33, v176
	v_add_f32_e32 v32, 1.0, v32
	v_max_f32_e32 v180, 0, v180
	v_mul_f32_e32 v33, 0xbfb8aa3b, v33
	v_mul_f32_e32 v49, v49, v178
	v_rcp_f32_e32 v32, v32
	v_sqrt_f32_e32 v180, v180
	v_exp_f32_e32 v33, v33
	v_mul_f32_e32 v49, 0x3fb8aa3b, v49
	v_exp_f32_e32 v49, v49
	v_add_f32_e32 v50, v50, v177
	v_mul_f32_e32 v50, 0xbfb8aa3b, v50
	v_lshl_add_u32 v179, v179, 1, s95
	v_exp_f32_e32 v50, v50
	v_add_u32_e32 v181, v179, v127
	v_mul_f32_e32 v180, v32, v180
	v_add_f32_e32 v33, 1.0, v33
	v_add_u32_e32 v179, v179, v128
	ds_read_u16 v181, v181
	ds_read_u16 v182, v179
	ds_read_u16 v183, v179 offset:144
	ds_read_u16 v184, v179 offset:288
	ds_read_u16 v185, v179 offset:432
	ds_read_u16 v186, v179 offset:576
	ds_read_u16 v187, v179 offset:720
	ds_read_u16 v188, v179 offset:864
	v_cndmask_b32_e64 v32, v180, v32, s[22:23]
	v_rcp_f32_e32 v180, v33
	v_fma_f32 v33, -v49, v49, 1.0
	s_waitcnt lgkmcnt(7)
; DI float bf2f(unsigned v) { return __uint_as_float(v << 16); }
; DI float sigmoidf_(float x) { return rcpf(1.f + __expf(-x)); }
; template <bool FINAL>
; DI void lru_unit(KA a, int l, int unit, LAS unsigned char* lds) {
;     ...
; #pragma unroll
;         for (int mb = 0; mb < 2; ++mb) {
;             float pp = 1.f, hh = 0.f;
; #pragma unroll
;             for (int i = 0; i < 16; ++i) {
;                 const int t = 32 * mb + 16 * h + i;
;                 const float rg = sigmoidf_(ar[mb][i] + ba_), ig = sigmoidf_(ai[mb][i] + bx_);
;                 const float la = c8 * rg;
;                 float av = __expf(la), mult = __builtin_amdgcn_sqrtf(fmaxf(1.f - av * av, 0.f));
;                 const float xcv = bf2f(xc[t * 72 + cl]);
;                 float bt = mult * ig * xcv;
;                 if (u.prompt && u.c == 0 && t == 0) { av = 0.f; bt = ig * xcv; }
;                 if (t >= nvalid) { av = 1.f; bt = 0.f; }
;                 hh = av * hh + bt; pp *= av;
;                 ar[mb][i] = pp; ai[mb][i] = hh;
;             }
;         }
	v_lshlrev_b32_e32 v181, 16, v181
	v_max_f32_e32 v33, 0, v33
	v_mul_f32_e32 v32, v32, v181
	v_sqrt_f32_e32 v181, v33
	v_add_f32_e32 v50, 1.0, v50
	v_add_f32_e32 v51, v51, v177
	v_rcp_f32_e32 v50, v50
	v_mul_f32_e32 v51, 0xbfb8aa3b, v51
	v_exp_f32_e32 v51, v51
	v_cndmask_b32_e64 v48, v48, 0, s[22:23]
	v_add_f32_e32 v34, v34, v176
	v_cndmask_b32_e64 v33, 1.0, v48, s[24:25]
	s_waitcnt lgkmcnt(6)
	v_lshlrev_b32_e32 v48, 16, v182
	v_mul_f32_e32 v180, v180, v181
	v_mul_f32_e32 v34, 0xbfb8aa3b, v34
	v_mul_f32_e32 v48, v180, v48
	v_exp_f32_e32 v180, v34
	v_mul_f32_e32 v34, v50, v178
	v_mul_f32_e32 v34, 0x3fb8aa3b, v34
	v_add_f32_e32 v51, 1.0, v51
	v_exp_f32_e32 v50, v34
	v_rcp_f32_e32 v51, v51
	v_cndmask_b32_e64 v32, 0, v32, s[24:25]
	v_fmac_f32_e32 v32, 0, v33
	v_cndmask_b32_e64 v48, 0, v48, s[26:27]
	v_cndmask_b32_e64 v49, 1.0, v49, s[26:27]
	v_add_f32_e32 v35, v35, v176
	v_fmac_f32_e32 v48, v49, v32
	v_mul_f32_e32 v34, v49, v33
	v_add_f32_e32 v49, 1.0, v180
	v_fma_f32 v180, -v50, v50, 1.0
	v_mul_f32_e32 v35, 0xbfb8aa3b, v35
	v_mul_f32_e32 v51, v51, v178
	v_max_f32_e32 v180, 0, v180
	v_exp_f32_e32 v35, v35
	v_mul_f32_e32 v51, 0x3fb8aa3b, v51
	v_rcp_f32_e32 v49, v49
	v_sqrt_f32_e32 v180, v180
	v_exp_f32_e32 v51, v51
	v_add_f32_e32 v52, v52, v177
	v_mul_f32_e32 v52, 0xbfb8aa3b, v52
	v_exp_f32_e32 v52, v52
	v_add_f32_e32 v35, 1.0, v35
	v_mul_f32_e32 v49, v49, v180
	v_rcp_f32_e32 v180, v35
	v_fma_f32 v35, -v51, v51, 1.0
	s_waitcnt lgkmcnt(5)
	v_lshlrev_b32_e32 v181, 16, v183
	v_max_f32_e32 v35, 0, v35
	v_mul_f32_e32 v49, v49, v181
	v_sqrt_f32_e32 v181, v35
	v_add_f32_e32 v52, 1.0, v52
	v_add_f32_e32 v53, v53, v177
	v_rcp_f32_e32 v52, v52
	v_mul_f32_e32 v53, 0xbfb8aa3b, v53
	v_exp_f32_e32 v53, v53
	v_cndmask_b32_e64 v49, 0, v49, s[28:29]
	v_cndmask_b32_e64 v50, 1.0, v50, s[28:29]
	v_add_f32_e32 v36, v36, v176
	v_fmac_f32_e32 v49, v50, v48
	v_mul_f32_e32 v35, v50, v34
	s_waitcnt lgkmcnt(4)
	v_lshlrev_b32_e32 v50, 16, v184
	v_mul_f32_e32 v180, v180, v181
	v_mul_f32_e32 v36, 0xbfb8aa3b, v36
	v_mul_f32_e32 v50, v180, v50
	v_exp_f32_e32 v180, v36
	v_mul_f32_e32 v36, v52, v178
	v_mul_f32_e32 v36, 0x3fb8aa3b, v36
	v_add_f32_e32 v53, 1.0, v53
	v_exp_f32_e32 v52, v36
	v_rcp_f32_e32 v53, v53
	v_cndmask_b32_e64 v50, 0, v50, s[30:31]
	v_cndmask_b32_e64 v51, 1.0, v51, s[30:31]
	v_add_f32_e32 v37, v37, v176
	v_fmac_f32_e32 v50, v51, v49
	v_mul_f32_e32 v36, v51, v35
	v_add_f32_e32 v51, 1.0, v180
	v_fma_f32 v180, -v52, v52, 1.0
	v_mul_f32_e32 v37, 0xbfb8aa3b, v37
	v_mul_f32_e32 v53, v53, v178
	v_max_f32_e32 v180, 0, v180
	v_exp_f32_e32 v37, v37
	v_mul_f32_e32 v53, 0x3fb8aa3b, v53
	v_rcp_f32_e32 v51, v51
	v_sqrt_f32_e32 v180, v180
	v_exp_f32_e32 v53, v53
	v_add_f32_e32 v54, v54, v177
	v_mul_f32_e32 v54, 0xbfb8aa3b, v54
	v_exp_f32_e32 v54, v54
	v_add_f32_e32 v37, 1.0, v37
	v_mul_f32_e32 v51, v51, v180
	v_rcp_f32_e32 v180, v37
	v_fma_f32 v37, -v53, v53, 1.0
	s_waitcnt lgkmcnt(3)
	v_lshlrev_b32_e32 v181, 16, v185
	v_max_f32_e32 v37, 0, v37
	v_mul_f32_e32 v51, v51, v181
	v_sqrt_f32_e32 v181, v37
	v_add_f32_e32 v54, 1.0, v54
	v_add_f32_e32 v55, v55, v177
	v_rcp_f32_e32 v54, v54
	v_mul_f32_e32 v55, 0xbfb8aa3b, v55
	v_exp_f32_e32 v55, v55
	v_cndmask_b32_e64 v51, 0, v51, s[34:35]
	v_cndmask_b32_e64 v52, 1.0, v52, s[34:35]
	v_add_f32_e32 v38, v38, v176
	v_fmac_f32_e32 v51, v52, v50
	v_mul_f32_e32 v37, v52, v36
	s_waitcnt lgkmcnt(2)
	v_lshlrev_b32_e32 v52, 16, v186
	v_mul_f32_e32 v180, v180, v181
	v_mul_f32_e32 v38, 0xbfb8aa3b, v38
	v_mul_f32_e32 v52, v180, v52
	v_exp_f32_e32 v180, v38
	v_mul_f32_e32 v38, v54, v178
	v_mul_f32_e32 v38, 0x3fb8aa3b, v38
	v_add_f32_e32 v55, 1.0, v55
	v_exp_f32_e32 v54, v38
	v_rcp_f32_e32 v55, v55
	v_cndmask_b32_e64 v52, 0, v52, s[36:37]
	v_cndmask_b32_e64 v53, 1.0, v53, s[36:37]
	v_add_f32_e32 v39, v39, v176
	v_fmac_f32_e32 v52, v53, v51
	v_mul_f32_e32 v38, v53, v37
	v_add_f32_e32 v53, 1.0, v180
	v_fma_f32 v180, -v54, v54, 1.0
	v_mul_f32_e32 v39, 0xbfb8aa3b, v39
	v_mul_f32_e32 v55, v55, v178
	v_max_f32_e32 v180, 0, v180
	v_exp_f32_e32 v39, v39
	v_mul_f32_e32 v55, 0x3fb8aa3b, v55
	v_rcp_f32_e32 v53, v53
	v_sqrt_f32_e32 v180, v180
	v_exp_f32_e32 v55, v55
	v_add_f32_e32 v56, v56, v177
	v_mul_f32_e32 v56, 0xbfb8aa3b, v56
	v_exp_f32_e32 v56, v56
	v_add_f32_e32 v39, 1.0, v39
	v_mul_f32_e32 v53, v53, v180
	v_rcp_f32_e32 v180, v39
	v_fma_f32 v39, -v55, v55, 1.0
	s_waitcnt lgkmcnt(1)
	v_lshlrev_b32_e32 v181, 16, v187
	v_max_f32_e32 v39, 0, v39
	v_mul_f32_e32 v53, v53, v181
	v_sqrt_f32_e32 v181, v39
	v_add_f32_e32 v56, 1.0, v56
	v_add_f32_e32 v57, v57, v177
	v_rcp_f32_e32 v56, v56
	v_mul_f32_e32 v57, 0xbfb8aa3b, v57
	v_exp_f32_e32 v57, v57
	v_cndmask_b32_e64 v53, 0, v53, s[38:39]
	v_cndmask_b32_e64 v54, 1.0, v54, s[38:39]
	v_add_f32_e32 v40, v40, v176
	v_fmac_f32_e32 v53, v54, v52
	v_mul_f32_e32 v39, v54, v38
	s_waitcnt lgkmcnt(0)
	v_lshlrev_b32_e32 v54, 16, v188
	v_mul_f32_e32 v180, v180, v181
	v_mul_f32_e32 v40, 0xbfb8aa3b, v40
	v_mul_f32_e32 v54, v180, v54
	v_exp_f32_e32 v180, v40
	v_mul_f32_e32 v40, v56, v178
	v_mul_f32_e32 v40, 0x3fb8aa3b, v40
	v_add_f32_e32 v57, 1.0, v57
	v_exp_f32_e32 v56, v40
	v_rcp_f32_e32 v57, v57
	v_cndmask_b32_e64 v54, 0, v54, s[40:41]
	v_cndmask_b32_e64 v55, 1.0, v55, s[40:41]
	v_add_f32_e32 v41, v41, v176
	v_fmac_f32_e32 v54, v55, v53
	v_mul_f32_e32 v40, v55, v39
	v_readlane_b32 s4, v255, 14
	v_readlane_b32 s5, v255, 15
	s_and_b64 vcc, exec, s[4:5]
	s_cbranch_vccnz .Llru_scan_cont
	s_waitcnt lgkmcnt(0)
	v_mov_b32_e32 v55, v54
	v_mov_b32_e32 v41, v40
	v_mov_b32_e32 v56, v54
	v_mov_b32_e32 v42, v40
	v_mov_b32_e32 v57, v54
	v_mov_b32_e32 v43, v40
	v_mov_b32_e32 v58, v54
	v_mov_b32_e32 v44, v40
	v_mov_b32_e32 v59, v54
	v_mov_b32_e32 v45, v40
	v_mov_b32_e32 v60, v54
	v_mov_b32_e32 v46, v40
	v_mov_b32_e32 v61, v54
	v_mov_b32_e32 v47, v40
	v_mov_b32_e32 v62, v54
	v_mov_b32_e32 v63, v40
	v_mov_b32_e32 v180, 0
	v_mov_b32_e32 v181, 1.0
	v_mov_b32_e32 v18, 0
	v_mov_b32_e32 v182, 1.0
	v_mov_b32_e32 v19, 0
	v_mov_b32_e32 v183, 1.0
	v_mov_b32_e32 v20, 0
	v_mov_b32_e32 v184, 1.0
	v_mov_b32_e32 v21, 0
	v_mov_b32_e32 v185, 1.0
	v_mov_b32_e32 v22, 0
	v_mov_b32_e32 v186, 1.0
	v_mov_b32_e32 v23, 0
	v_mov_b32_e32 v187, 1.0
	v_mov_b32_e32 v24, 0
	v_mov_b32_e32 v188, 1.0
	v_mov_b32_e32 v25, 0
	v_mov_b32_e32 v179, 1.0
	v_mov_b32_e32 v26, 0
	v_mov_b32_e32 v189, 1.0
	v_mov_b32_e32 v27, 0
	v_mov_b32_e32 v190, 1.0
	v_mov_b32_e32 v28, 0
	v_mov_b32_e32 v191, 1.0
	v_mov_b32_e32 v29, 0
	v_mov_b32_e32 v192, 1.0
	v_mov_b32_e32 v30, 0
	v_mov_b32_e32 v193, 1.0
	v_mov_b32_e32 v31, 0
	v_mov_b32_e32 v176, 1.0
	v_mov_b32_e32 v177, 0
	v_mov_b32_e32 v178, 1.0
	s_branch .Llru_scan_end
